# v23: v22 + small_gemm K loops with loads up front + GEMM phase prologue drain removed (tile epilogues still barrier-aligned) - reference point for the alignment change in v24
# speedup vs baseline: 1.0268x; 1.0139x over previous
; #define PG8_STAGE(bufoff, gbase, voff) do { _Pragma("unroll") for (int _i = 0; _i < 2; ++_i) \
;         __builtin_amdgcn_global_load_lds((const unsigned*)((const char*)(gbase) + (voff)[_i]), (PG8_LAS unsigned*)(lds + (bufoff) + ldsw + _i * 8192), 16, 0, 0); } while (0)
; #define PG8_WAIT_V(n) asm volatile("s_waitcnt vmcnt(" #n ")" ::: "memory")
; #define PG8_BAR __builtin_amdgcn_s_barrier()
; template <class Epi, class Sched, bool ALIGN_EPI = false, bool SP2 = false>
; __device__ __forceinline__ void gemm_phase(PG8_LAS unsigned char* lds, const Gemm g, const Sched& S, const Epi& E) {
;     ...
;     const unsigned ldsw = (unsigned)wid * 1024u;
;     const int aoff = lds_byte(wr * 64 + fr, fq * 8), boff = lds_byte(wc * 32 + fr, fq * 8);
;     ...
;         PG8_STAGE(PG8_SB(1, 0), cB + kstep, voffB); PG8_STAGE(PG8_SA(1, 0), cA + kstep, voffA); PG8_STAGE(PG8_SB(1, 1), cB + hstep + kstep, voffB);
;         PG8_WAIT_V(6); PG8_BAR;
.LBB0_674:
	s_cmp_eq_u32 s75, 15
	s_mov_b32 s11, 0x40000
	s_cselect_b32 s22, 0x80000, s11
	s_add_i32 m0, s76, 0x18000
	v_lshl_add_u64 v[0:1], v[0:1], 0, s[44:45]
	s_waitcnt vmcnt(2)
	s_barrier
	global_load_lds_dwordx4 v[0:1], off
	v_lshl_add_u64 v[0:1], v[2:3], 0, s[44:45]
	s_add_i32 m0, s76, 0x1a000
	s_add_i32 s73, s76, 0x8000
	global_load_lds_dwordx4 v[0:1], off
	v_lshl_add_u64 v[0:1], v[8:9], 0, s[44:45]
	s_mov_b32 m0, s73
	s_add_i32 s68, s76, 0xa000
	global_load_lds_dwordx4 v[0:1], off
	v_lshl_add_u64 v[0:1], v[10:11], 0, s[44:45]
	s_mov_b32 m0, s68
	v_lshrrev_b32_e32 v20, 1, v18
	global_load_lds_dwordx4 v[0:1], off
	s_add_i32 m0, s76, 0x1c000
	v_lshl_add_u64 v[0:1], v[4:5], 0, s[44:45]
	global_load_lds_dwordx4 v[0:1], off
	v_lshl_add_u64 v[0:1], v[6:7], 0, s[44:45]
	s_add_i32 m0, s76, 0x1e000
	v_and_b32_e32 v20, 24, v20
	global_load_lds_dwordx4 v[0:1], off
	v_and_b32_e32 v19, 15, v18
	v_lshlrev_b32_e32 v21, 1, v20
	v_lshlrev_b32_e32 v18, 2, v18
	s_lshl_b32 s0, s0, 5
	s_lshr_b32 s87, s64, 6
	v_lshl_or_b32 v160, s1, 6, v19
	v_lshl_or_b32 v19, v19, 6, v21
	s_lshl_b32 s1, s1, 13
	v_and_b32_e32 v18, 32, v18
	s_and_b32 s0, s0, 0x60
	v_bitop3_b32 v21, v19, s1, v18 bitop3:0xde
	s_lshl_b32 s1, s0, 7
	s_add_i32 s72, s87, -2
	s_cmpk_lt_u32 s10, 0x100
	s_cselect_b64 s[94:95], -1, 0
	s_lshr_b32 s42, s54, 5
	v_cvt_f32_u32_e32 v0, s42
	s_lshr_b32 s63, s28, 3
	v_or_b32_e32 v168, s0, v20
	s_add_i32 s0, s63, 1
	v_rcp_iflag_f32_e32 v0, v0
	s_ashr_i32 s10, s69, 31
	s_and_b32 s11, s28, 7
	v_writelane_b32 v250, s0, 5
	v_mul_f32_e32 v0, 0x4f7ffffe, v0
	s_add_i32 s0, s24, -1
	v_cvt_u32_f32_e32 v0, v0
	s_cmp_lt_u32 s0, 2
	v_bitop3_b32 v161, v19, s1, v18 bitop3:0xde
	s_cselect_b64 s[0:1], -1, 0
	v_writelane_b32 v251, s0, 63
	s_add_u32 s22, s82, s22
	s_addc_u32 s23, s83, 0
	v_writelane_b32 v250, s1, 0
	v_readfirstlane_b32 s1, v0
	v_add_u32_e32 v0, v14, v12
	s_sub_i32 s0, 0, s42
	v_add_lshl_u32 v0, v0, v13, 1
	v_mov_b32_e32 v1, v65
	s_waitcnt vmcnt(6)
	s_mul_i32 s0, s0, s1
	v_lshl_add_u64 v[136:137], s[4:5], 0, v[0:1]
	v_add_u32_e32 v0, v17, v15
	s_mul_hi_u32 s0, s1, s0
	v_add_lshl_u32 v0, v0, v16, 1
	s_mov_b32 s71, 0
	s_mov_b32 s29, s5
	s_add_i32 s0, s1, s0
	v_lshl_add_u64 v[138:139], s[4:5], 0, v[0:1]
	v_add_u32_e32 v169, 0, v21
	s_barrier
	v_writelane_b32 v250, s0, 3
	s_branch .LBB0_677

; __device__ __forceinline__ void small_gemm(LAS unsigned char* lds, unsigned char* ws, size_t oA, size_t oB, int N_out, int K, int kind, size_t oO, int ldc, int G) {
;     ...
;         if (paired) {
; #pragma unroll 4
;             for (int k = 0; k < kslice; k += 32) {
;                 const bf16x8 a0 = *(const bf16x8*)(ap + k), a1 = *(const bf16x8*)(ap + k + 16);
;                 const bf16x8 b0 = *(const bf16x8*)(bp + k), b1 = *(const bf16x8*)(bp + k + 16), c0 = *(const bf16x8*)(bp + (size_t)128 * K + k), c1 = *(const bf16x8*)(bp + (size_t)128 * K + k + 16);
;                 ca = __builtin_amdgcn_mfma_f32_32x32x16_bf16(a0, b0, ca, 0, 0, 0); ca = __builtin_amdgcn_mfma_f32_32x32x16_bf16(a1, b1, ca, 0, 0, 0);
;                 cb = __builtin_amdgcn_mfma_f32_32x32x16_bf16(a0, c0, cb, 0, 0, 0); cb = __builtin_amdgcn_mfma_f32_32x32x16_bf16(a1, c1, cb, 0, 0, 0);
;             }
;         } else {
; #pragma unroll 4
;             for (int k = 0; k < kslice; k += 32) {
;                 const bf16x8 a0 = *(const bf16x8*)(ap + k), a1 = *(const bf16x8*)(ap + k + 16);
;                 const bf16x8 b0 = *(const bf16x8*)(bp + k), b1 = *(const bf16x8*)(bp + k + 16);
;                 ca = __builtin_amdgcn_mfma_f32_32x32x16_bf16(a0, b0, ca, 0, 0, 0); ca = __builtin_amdgcn_mfma_f32_32x32x16_bf16(a1, b1, ca, 0, 0, 0);
;             }
;         }
.LBB0_1069:
	s_add_i32 s1, s0, 0x80
	s_cmp_gt_u32 s1, s10
	s_cbranch_scc1 .Lsg_u_tail
	global_load_dwordx4 v[92:95], v[18:19], off offset:-32
	global_load_dwordx4 v[96:99], v[16:17], off offset:-32
	global_load_dwordx4 v[100:103], v[18:19], off
	global_load_dwordx4 v[104:107], v[16:17], off
	global_load_dwordx4 v[108:111], v[18:19], off offset:32
	global_load_dwordx4 v[112:115], v[16:17], off offset:32
	global_load_dwordx4 v[116:119], v[18:19], off offset:64
	global_load_dwordx4 v[120:123], v[16:17], off offset:64
	global_load_dwordx4 v[124:127], v[18:19], off offset:96
	global_load_dwordx4 v[128:131], v[16:17], off offset:96
	global_load_dwordx4 v[132:135], v[18:19], off offset:128
	global_load_dwordx4 v[136:139], v[16:17], off offset:128
	global_load_dwordx4 v[140:143], v[18:19], off offset:160
	global_load_dwordx4 v[144:147], v[16:17], off offset:160
	global_load_dwordx4 v[148:151], v[18:19], off offset:192
	global_load_dwordx4 v[152:155], v[16:17], off offset:192
	s_mov_b64 vcc, 0x100
	s_mov_b32 s0, s1
	v_lshl_add_u64 v[18:19], v[18:19], 0, vcc
	v_lshl_add_u64 v[16:17], v[16:17], 0, vcc
	s_waitcnt vmcnt(14)
	v_mfma_f32_32x32x16_bf16 v[0:15], v[92:95], v[96:99], v[0:15]
	s_waitcnt vmcnt(12)
	v_mfma_f32_32x32x16_bf16 v[0:15], v[100:103], v[104:107], v[0:15]
	s_waitcnt vmcnt(10)
	v_mfma_f32_32x32x16_bf16 v[0:15], v[108:111], v[112:115], v[0:15]
	s_waitcnt vmcnt(8)
	v_mfma_f32_32x32x16_bf16 v[0:15], v[116:119], v[120:123], v[0:15]
	s_waitcnt vmcnt(6)
	v_mfma_f32_32x32x16_bf16 v[0:15], v[124:127], v[128:131], v[0:15]
	s_waitcnt vmcnt(4)
	v_mfma_f32_32x32x16_bf16 v[0:15], v[132:135], v[136:139], v[0:15]
	s_waitcnt vmcnt(2)
	v_mfma_f32_32x32x16_bf16 v[0:15], v[140:143], v[144:147], v[0:15]
	s_waitcnt vmcnt(0)
	v_mfma_f32_32x32x16_bf16 v[0:15], v[148:151], v[152:155], v[0:15]
	s_branch .LBB0_1069
.Lsg_u_tail:
	s_cmp_lt_u32 s0, s10
	s_cbranch_scc0 .Lsg_u_done
.Lsg_u_tail_loop:
	global_load_dwordx4 v[20:23], v[18:19], off offset:-32
	global_load_dwordx4 v[24:27], v[16:17], off offset:-32
	global_load_dwordx4 v[28:31], v[18:19], off
	s_add_i32 s0, s0, 32
	s_cmp_lt_u32 s0, s10
	v_lshl_add_u64 v[18:19], v[18:19], 0, 64
	s_waitcnt vmcnt(1)
	v_mfma_f32_32x32x16_bf16 v[0:15], v[20:23], v[24:27], v[0:15]
	global_load_dwordx4 v[20:23], v[16:17], off
	v_lshl_add_u64 v[16:17], v[16:17], 0, 64
	s_waitcnt vmcnt(0)
	v_mfma_f32_32x32x16_bf16 v[0:15], v[28:31], v[20:23], v[0:15]
	s_cbranch_scc1 .Lsg_u_tail_loop
.Lsg_u_done:
	s_mov_b64 s[0:1], 0
.LBB0_1071:
	v_mov_b32_e32 v31, 0
	s_and_b64 vcc, exec, s[0:1]
	v_mov_b32_e32 v30, v31
	v_mov_b32_e32 v29, v31
	v_mov_b32_e32 v28, v31
	v_mov_b32_e32 v27, v31
	v_mov_b32_e32 v26, v31
	v_mov_b32_e32 v25, v31
	v_mov_b32_e32 v24, v31
	v_mov_b32_e32 v23, v31
	v_mov_b32_e32 v22, v31
	v_mov_b32_e32 v21, v31
	v_mov_b32_e32 v20, v31
	v_mov_b32_e32 v19, v31
	v_mov_b32_e32 v18, v31
	v_mov_b32_e32 v17, v31
	v_mov_b32_e32 v16, v31
	s_cbranch_vccz .LBB0_1074
	v_lshl_add_u64 v[0:1], v[36:37], 1, v[162:163]
	v_mad_u64_u32 v[32:33], s[0:1], s64, v0, v[74:75]
	v_mad_i64_i32 v[36:37], s[0:1], s11, v36, v[74:75]
	v_mov_b32_e32 v0, 0
	v_mad_i32_i24 v33, s64, v1, v33
	v_lshl_add_u64 v[34:35], v[76:77], 0, v[64:65]
	s_mov_b32 s0, 0
	v_mov_b32_e32 v1, v0
	v_mov_b32_e32 v2, v0
	v_mov_b32_e32 v3, v0
	v_mov_b32_e32 v4, v0
	v_mov_b32_e32 v5, v0
	v_mov_b32_e32 v6, v0
	v_mov_b32_e32 v7, v0
	v_mov_b32_e32 v8, v0
	v_mov_b32_e32 v9, v0
	v_mov_b32_e32 v10, v0
	v_mov_b32_e32 v11, v0
	v_mov_b32_e32 v12, v0
	v_mov_b32_e32 v13, v0
	v_mov_b32_e32 v14, v0
	v_mov_b32_e32 v15, v0
	v_mov_b32_e32 v16, v0
	v_mov_b32_e32 v17, v0
	v_mov_b32_e32 v18, v0
	v_mov_b32_e32 v19, v0
	v_mov_b32_e32 v20, v0
	v_mov_b32_e32 v21, v0
	v_mov_b32_e32 v22, v0
	v_mov_b32_e32 v23, v0
	v_mov_b32_e32 v24, v0
	v_mov_b32_e32 v25, v0
	v_mov_b32_e32 v26, v0
	v_mov_b32_e32 v27, v0
	v_mov_b32_e32 v28, v0
	v_mov_b32_e32 v29, v0
	v_mov_b32_e32 v30, v0
	v_mov_b32_e32 v31, v0
.LBB0_1073:
	s_add_i32 s1, s0, 0x80
	s_cmp_gt_u32 s1, s10
	s_cbranch_scc1 .Lsg_p_tail
	global_load_dwordx4 v[92:95], v[34:35], off offset:-32
	global_load_dwordx4 v[96:99], v[36:37], off offset:-32
	global_load_dwordx4 v[100:103], v[32:33], off offset:-32
	global_load_dwordx4 v[104:107], v[34:35], off
	global_load_dwordx4 v[108:111], v[36:37], off
	global_load_dwordx4 v[112:115], v[32:33], off
	global_load_dwordx4 v[116:119], v[34:35], off offset:32
	global_load_dwordx4 v[120:123], v[36:37], off offset:32
	global_load_dwordx4 v[124:127], v[32:33], off offset:32
	global_load_dwordx4 v[128:131], v[34:35], off offset:64
	global_load_dwordx4 v[132:135], v[36:37], off offset:64
	global_load_dwordx4 v[136:139], v[32:33], off offset:64
	global_load_dwordx4 v[140:143], v[34:35], off offset:96
	global_load_dwordx4 v[144:147], v[36:37], off offset:96
	global_load_dwordx4 v[148:151], v[32:33], off offset:96
	global_load_dwordx4 v[152:155], v[34:35], off offset:128
	global_load_dwordx4 v[156:159], v[36:37], off offset:128
	global_load_dwordx4 v[168:171], v[32:33], off offset:128
	global_load_dwordx4 v[172:175], v[34:35], off offset:160
	global_load_dwordx4 v[176:179], v[36:37], off offset:160
	global_load_dwordx4 v[180:183], v[32:33], off offset:160
	global_load_dwordx4 v[184:187], v[34:35], off offset:192
	global_load_dwordx4 v[188:191], v[36:37], off offset:192
	global_load_dwordx4 v[192:195], v[32:33], off offset:192
	s_mov_b64 vcc, 0x100
	s_mov_b32 s0, s1
	v_lshl_add_u64 v[34:35], v[34:35], 0, vcc
	v_lshl_add_u64 v[36:37], v[36:37], 0, vcc
	v_lshl_add_u64 v[32:33], v[32:33], 0, vcc
	s_waitcnt vmcnt(22)
	v_mfma_f32_32x32x16_bf16 v[0:15], v[92:95], v[96:99], v[0:15]
	s_waitcnt vmcnt(21)
	v_mfma_f32_32x32x16_bf16 v[16:31], v[92:95], v[100:103], v[16:31]
	s_waitcnt vmcnt(19)
	v_mfma_f32_32x32x16_bf16 v[0:15], v[104:107], v[108:111], v[0:15]
	s_waitcnt vmcnt(18)
	v_mfma_f32_32x32x16_bf16 v[16:31], v[104:107], v[112:115], v[16:31]
	s_waitcnt vmcnt(16)
	v_mfma_f32_32x32x16_bf16 v[0:15], v[116:119], v[120:123], v[0:15]
	s_waitcnt vmcnt(15)
	v_mfma_f32_32x32x16_bf16 v[16:31], v[116:119], v[124:127], v[16:31]
	s_waitcnt vmcnt(13)
	v_mfma_f32_32x32x16_bf16 v[0:15], v[128:131], v[132:135], v[0:15]
	s_waitcnt vmcnt(12)
	v_mfma_f32_32x32x16_bf16 v[16:31], v[128:131], v[136:139], v[16:31]
	s_waitcnt vmcnt(10)
	v_mfma_f32_32x32x16_bf16 v[0:15], v[140:143], v[144:147], v[0:15]
	s_waitcnt vmcnt(9)
	v_mfma_f32_32x32x16_bf16 v[16:31], v[140:143], v[148:151], v[16:31]
	s_waitcnt vmcnt(7)
	v_mfma_f32_32x32x16_bf16 v[0:15], v[152:155], v[156:159], v[0:15]
	s_waitcnt vmcnt(6)
	v_mfma_f32_32x32x16_bf16 v[16:31], v[152:155], v[168:171], v[16:31]
	s_waitcnt vmcnt(4)
	v_mfma_f32_32x32x16_bf16 v[0:15], v[172:175], v[176:179], v[0:15]
	s_waitcnt vmcnt(3)
	v_mfma_f32_32x32x16_bf16 v[16:31], v[172:175], v[180:183], v[16:31]
	s_waitcnt vmcnt(1)
	v_mfma_f32_32x32x16_bf16 v[0:15], v[184:187], v[188:191], v[0:15]
	s_waitcnt vmcnt(0)
	v_mfma_f32_32x32x16_bf16 v[16:31], v[184:187], v[192:195], v[16:31]
	s_branch .LBB0_1073

; __device__ __forceinline__ void small_gemm(LAS unsigned char* lds, unsigned char* ws, size_t oA, size_t oB, int N_out, int K, int kind, size_t oO, int ldc, int G) {
;     ...
;         }
; #pragma unroll
;         for (int r = 0; r < 16; ++r) { PA[(kq * 16 + r) * 64 + lane] = ca[r]; if (paired) PB[(kq * 16 + r) * 64 + lane] = cb[r]; }
.Lsg_p_done:
.LBB0_1074:
	s_and_b64 vcc, exec, s[90:91]
	s_nop 5
	ds_write_b32 v80, v0
	s_cbranch_vccz .LBB0_1076
	s_cbranch_execz .LBB0_1077
	s_branch .LBB0_1078
